# final rmsnorm and norm_x loops: 4 rows in flight per wave, norm weights hoisted (f32 math unchanged)
# baseline (speedup 1.0000x reference)
; DI void phase_norm_x(const float* src_lo, const float* src_hi, int split_row, int row0, bf16_t* xb, int gw, int ngw, int lane) {
;     for (int r = gw; r < MC; r += ngw) {
;         const int R = row0 + r; const float* src = (R < split_row ? src_lo + (size_t)R * 1024 : src_hi + (size_t)(R - split_row) * 1024);
;         f32x4 v[4]; float ss = 0.f;
; #pragma unroll
;         for (int j = 0; j < 4; ++j) { v[j] = *(const f32x4*)(src + j * 256 + lane * 4); ss += v[j][0] * v[j][0] + v[j][1] * v[j][1] + v[j][2] * v[j][2] + v[j][3] * v[j][3]; }
;         ss = wave_sum(ss); const float rs = rsqrtf(ldexpf(ss + 1024.0f * EPS, -10));
.Lnx1_top:
	v_readfirstlane_b32 s0, v2
	s_mul_i32 s7, s24, 3
	s_add_u32 s7, s7, s0
	s_cmp_gt_u32 s7, s2
	s_cbranch_scc1 .Lnx1_rem
	v_add_u32_e32 v3, s8, v2
	v_cmp_gt_i32_e32 vcc, s61, v3
	v_add_u32_e32 v3, 0xffff4000, v6
	v_add_u32_e32 v2, s24, v2
	v_cndmask_b32_e32 v17, 0, v7, vcc
	v_cndmask_b32_e32 v16, v3, v6, vcc
	v_lshlrev_b64 v[16:17], 12, v[16:17]
	v_lshl_add_u64 v[104:105], v[4:5], 0, v[16:17]
	v_lshl_add_u64 v[6:7], v[6:7], 0, s[24:25]
	global_load_dwordx4 v[40:43], v[104:105], off
	global_load_dwordx4 v[44:47], v[104:105], off offset:1024
	global_load_dwordx4 v[48:51], v[104:105], off offset:2048
	global_load_dwordx4 v[52:55], v[104:105], off offset:3072
	v_add_u32_e32 v3, s8, v2
	v_cmp_gt_i32_e32 vcc, s61, v3
	v_add_u32_e32 v3, 0xffff4000, v6
	v_add_u32_e32 v2, s24, v2
	v_cndmask_b32_e32 v17, 0, v7, vcc
	v_cndmask_b32_e32 v16, v3, v6, vcc
	v_lshlrev_b64 v[16:17], 12, v[16:17]
	v_lshl_add_u64 v[106:107], v[4:5], 0, v[16:17]
	v_lshl_add_u64 v[6:7], v[6:7], 0, s[24:25]
	global_load_dwordx4 v[56:59], v[106:107], off
	global_load_dwordx4 v[60:63], v[106:107], off offset:1024
	global_load_dwordx4 v[64:67], v[106:107], off offset:2048
	global_load_dwordx4 v[68:71], v[106:107], off offset:3072
	v_add_u32_e32 v3, s8, v2
	v_cmp_gt_i32_e32 vcc, s61, v3
	v_add_u32_e32 v3, 0xffff4000, v6
	v_add_u32_e32 v2, s24, v2
	v_cndmask_b32_e32 v17, 0, v7, vcc
	v_cndmask_b32_e32 v16, v3, v6, vcc
	v_lshlrev_b64 v[16:17], 12, v[16:17]
	v_lshl_add_u64 v[108:109], v[4:5], 0, v[16:17]
	v_lshl_add_u64 v[6:7], v[6:7], 0, s[24:25]
	global_load_dwordx4 v[72:75], v[108:109], off
	global_load_dwordx4 v[76:79], v[108:109], off offset:1024
	global_load_dwordx4 v[80:83], v[108:109], off offset:2048
	global_load_dwordx4 v[84:87], v[108:109], off offset:3072
	v_add_u32_e32 v3, s8, v2
	v_cmp_gt_i32_e32 vcc, s61, v3
	v_add_u32_e32 v3, 0xffff4000, v6
	v_add_u32_e32 v2, s24, v2
	v_cndmask_b32_e32 v17, 0, v7, vcc
	v_cndmask_b32_e32 v16, v3, v6, vcc
	v_lshlrev_b64 v[16:17], 12, v[16:17]
	v_lshl_add_u64 v[110:111], v[4:5], 0, v[16:17]
	v_lshl_add_u64 v[6:7], v[6:7], 0, s[24:25]
	global_load_dwordx4 v[88:91], v[110:111], off
	global_load_dwordx4 v[92:95], v[110:111], off offset:1024
	global_load_dwordx4 v[96:99], v[110:111], off offset:2048
	global_load_dwordx4 v[100:103], v[110:111], off offset:3072
	s_waitcnt vmcnt(12)
	v_mul_f32_e32 v112, v40, v40
	v_fmac_f32_e32 v112, v41, v41
	v_fmac_f32_e32 v112, v42, v42
	v_fmac_f32_e32 v112, v43, v43
	v_fmac_f32_e32 v112, v44, v44
	v_fmac_f32_e32 v112, v45, v45
	v_fmac_f32_e32 v112, v46, v46
	v_fmac_f32_e32 v112, v47, v47
	v_fmac_f32_e32 v112, v48, v48
	v_fmac_f32_e32 v112, v49, v49
	v_fmac_f32_e32 v112, v50, v50
	v_fmac_f32_e32 v112, v51, v51
	v_fmac_f32_e32 v112, v52, v52
	v_fmac_f32_e32 v112, v53, v53
	v_fmac_f32_e32 v112, v54, v54
	v_fmac_f32_e32 v112, v55, v55
	s_waitcnt vmcnt(8)
	v_mul_f32_e32 v113, v56, v56
	v_fmac_f32_e32 v113, v57, v57
	v_fmac_f32_e32 v113, v58, v58
	v_fmac_f32_e32 v113, v59, v59
	v_fmac_f32_e32 v113, v60, v60
	v_fmac_f32_e32 v113, v61, v61
	v_fmac_f32_e32 v113, v62, v62
	v_fmac_f32_e32 v113, v63, v63
	v_fmac_f32_e32 v113, v64, v64
	v_fmac_f32_e32 v113, v65, v65
	v_fmac_f32_e32 v113, v66, v66
	v_fmac_f32_e32 v113, v67, v67
	v_fmac_f32_e32 v113, v68, v68
	v_fmac_f32_e32 v113, v69, v69
	v_fmac_f32_e32 v113, v70, v70
	v_fmac_f32_e32 v113, v71, v71
	s_waitcnt vmcnt(4)
	v_mul_f32_e32 v114, v72, v72
	v_fmac_f32_e32 v114, v73, v73
	v_fmac_f32_e32 v114, v74, v74
	v_fmac_f32_e32 v114, v75, v75
	v_fmac_f32_e32 v114, v76, v76
	v_fmac_f32_e32 v114, v77, v77
	v_fmac_f32_e32 v114, v78, v78
	v_fmac_f32_e32 v114, v79, v79
	v_fmac_f32_e32 v114, v80, v80
	v_fmac_f32_e32 v114, v81, v81
	v_fmac_f32_e32 v114, v82, v82
	v_fmac_f32_e32 v114, v83, v83
	v_fmac_f32_e32 v114, v84, v84
	v_fmac_f32_e32 v114, v85, v85
	v_fmac_f32_e32 v114, v86, v86
	v_fmac_f32_e32 v114, v87, v87
	s_waitcnt vmcnt(0)
	v_mul_f32_e32 v115, v88, v88
	v_fmac_f32_e32 v115, v89, v89
	v_fmac_f32_e32 v115, v90, v90
	v_fmac_f32_e32 v115, v91, v91
	v_fmac_f32_e32 v115, v92, v92
	v_fmac_f32_e32 v115, v93, v93
	v_fmac_f32_e32 v115, v94, v94
	v_fmac_f32_e32 v115, v95, v95
	v_fmac_f32_e32 v115, v96, v96
	v_fmac_f32_e32 v115, v97, v97
	v_fmac_f32_e32 v115, v98, v98
	v_fmac_f32_e32 v115, v99, v99
	v_fmac_f32_e32 v115, v100, v100
	v_fmac_f32_e32 v115, v101, v101
	v_fmac_f32_e32 v115, v102, v102
	v_fmac_f32_e32 v115, v103, v103
	ds_bpermute_b32 v116, v1, v112
	ds_bpermute_b32 v117, v1, v113
	ds_bpermute_b32 v118, v1, v114
	ds_bpermute_b32 v119, v1, v115
	s_waitcnt lgkmcnt(0)
	v_add_f32_e32 v112, v112, v116
	v_add_f32_e32 v113, v113, v117
	v_add_f32_e32 v114, v114, v118
	v_add_f32_e32 v115, v115, v119
	ds_bpermute_b32 v116, v11, v112
	ds_bpermute_b32 v117, v11, v113
	ds_bpermute_b32 v118, v11, v114
	ds_bpermute_b32 v119, v11, v115
	s_waitcnt lgkmcnt(0)
	v_add_f32_e32 v112, v112, v116
	v_add_f32_e32 v113, v113, v117
	v_add_f32_e32 v114, v114, v118
	v_add_f32_e32 v115, v115, v119
	ds_bpermute_b32 v116, v12, v112
	ds_bpermute_b32 v117, v12, v113
	ds_bpermute_b32 v118, v12, v114
	ds_bpermute_b32 v119, v12, v115
	s_waitcnt lgkmcnt(0)
	v_add_f32_e32 v112, v112, v116
	v_add_f32_e32 v113, v113, v117
	v_add_f32_e32 v114, v114, v118
	v_add_f32_e32 v115, v115, v119
	ds_bpermute_b32 v116, v13, v112
	ds_bpermute_b32 v117, v13, v113
	ds_bpermute_b32 v118, v13, v114
	ds_bpermute_b32 v119, v13, v115
	s_waitcnt lgkmcnt(0)
	v_add_f32_e32 v112, v112, v116
	v_add_f32_e32 v113, v113, v117
	v_add_f32_e32 v114, v114, v118
	v_add_f32_e32 v115, v115, v119
	ds_bpermute_b32 v116, v14, v112
	ds_bpermute_b32 v117, v14, v113
	ds_bpermute_b32 v118, v14, v114
	ds_bpermute_b32 v119, v14, v115
	s_waitcnt lgkmcnt(0)
; DI unsigned pk2(float lo, float hi) { const f32x2_t v = {lo, hi}; return __builtin_bit_cast(unsigned, __builtin_convertvector(v, bf16x2_t)); }
; DI void phase_norm_x(const float* src_lo, const float* src_hi, int split_row, int row0, bf16_t* xb, int gw, int ngw, int lane) {
;     ...
;         ss = wave_sum(ss); const float rs = rsqrtf(ldexpf(ss + 1024.0f * EPS, -10));
; #pragma unroll
;         for (int j = 0; j < 4; ++j) { u32x2 w; w.x = pk2(v[j][0] * rs, v[j][1] * rs); w.y = pk2(v[j][2] * rs, v[j][3] * rs); *(u32x2*)(xb + (size_t)r * 1024 + j * 256 + lane * 4) = w; }
;     }
	v_add_f32_e32 v112, v112, v116
	v_add_f32_e32 v113, v113, v117
	v_add_f32_e32 v114, v114, v118
	v_add_f32_e32 v115, v115, v119
	ds_bpermute_b32 v116, v15, v112
	ds_bpermute_b32 v117, v15, v113
	ds_bpermute_b32 v118, v15, v114
	ds_bpermute_b32 v119, v15, v115
	s_waitcnt lgkmcnt(0)
	v_add_f32_e32 v112, v112, v116
	v_add_f32_e32 v113, v113, v117
	v_add_f32_e32 v114, v114, v118
	v_add_f32_e32 v115, v115, v119
	v_add_f32_e32 v112, 0x3a8637bd, v112
	v_ldexp_f32 v112, v112, -10
	v_cmp_gt_f32_e32 vcc, s19, v112
	v_mul_f32_e32 v116, 0x4b800000, v112
	s_nop 0
	v_cndmask_b32_e32 v112, v112, v116, vcc
	v_rsq_f32_e32 v112, v112
	s_nop 0
	v_mul_f32_e32 v116, 0x45800000, v112
	v_cndmask_b32_e32 v120, v112, v116, vcc
	v_add_f32_e32 v113, 0x3a8637bd, v113
	v_ldexp_f32 v113, v113, -10
	v_cmp_gt_f32_e32 vcc, s19, v113
	v_mul_f32_e32 v116, 0x4b800000, v113
	s_nop 0
	v_cndmask_b32_e32 v113, v113, v116, vcc
	v_rsq_f32_e32 v113, v113
	s_nop 0
	v_mul_f32_e32 v116, 0x45800000, v113
	v_cndmask_b32_e32 v122, v113, v116, vcc
	v_add_f32_e32 v114, 0x3a8637bd, v114
	v_ldexp_f32 v114, v114, -10
	v_cmp_gt_f32_e32 vcc, s19, v114
	v_mul_f32_e32 v116, 0x4b800000, v114
	s_nop 0
	v_cndmask_b32_e32 v114, v114, v116, vcc
	v_rsq_f32_e32 v114, v114
	s_nop 0
	v_mul_f32_e32 v116, 0x45800000, v114
	v_cndmask_b32_e32 v124, v114, v116, vcc
	v_add_f32_e32 v115, 0x3a8637bd, v115
	v_ldexp_f32 v115, v115, -10
	v_cmp_gt_f32_e32 vcc, s19, v115
	v_mul_f32_e32 v116, 0x4b800000, v115
	s_nop 0
	v_cndmask_b32_e32 v115, v115, v116, vcc
	v_rsq_f32_e32 v115, v115
	s_nop 0
	v_mul_f32_e32 v116, 0x45800000, v115
	v_cndmask_b32_e32 v126, v115, v116, vcc
	v_pk_mul_f32 v[16:17], v[40:41], v[120:121] op_sel_hi:[1,0]
	v_pk_mul_f32 v[18:19], v[42:43], v[120:121] op_sel_hi:[1,0]
	v_cvt_pk_bf16_f32 v16, v16, v17
	v_cvt_pk_bf16_f32 v17, v18, v19
	global_store_dwordx2 v[8:9], v[16:17], off offset:-1024
	v_pk_mul_f32 v[16:17], v[44:45], v[120:121] op_sel_hi:[1,0]
	v_pk_mul_f32 v[18:19], v[46:47], v[120:121] op_sel_hi:[1,0]
	v_cvt_pk_bf16_f32 v16, v16, v17
	v_cvt_pk_bf16_f32 v17, v18, v19
	global_store_dwordx2 v[8:9], v[16:17], off offset:-512
	v_pk_mul_f32 v[16:17], v[48:49], v[120:121] op_sel_hi:[1,0]
	v_pk_mul_f32 v[18:19], v[50:51], v[120:121] op_sel_hi:[1,0]
	v_cvt_pk_bf16_f32 v16, v16, v17
	v_cvt_pk_bf16_f32 v17, v18, v19
	global_store_dwordx2 v[8:9], v[16:17], off
	v_pk_mul_f32 v[16:17], v[52:53], v[120:121] op_sel_hi:[1,0]
	v_pk_mul_f32 v[18:19], v[54:55], v[120:121] op_sel_hi:[1,0]
	v_cvt_pk_bf16_f32 v16, v16, v17
	v_cvt_pk_bf16_f32 v17, v18, v19
	global_store_dwordx2 v[8:9], v[16:17], off offset:512
	v_lshl_add_u64 v[8:9], v[8:9], 0, s[62:63]
	v_pk_mul_f32 v[16:17], v[56:57], v[122:123] op_sel_hi:[1,0]
	v_pk_mul_f32 v[18:19], v[58:59], v[122:123] op_sel_hi:[1,0]
	v_cvt_pk_bf16_f32 v16, v16, v17
	v_cvt_pk_bf16_f32 v17, v18, v19
	global_store_dwordx2 v[8:9], v[16:17], off offset:-1024
	v_pk_mul_f32 v[16:17], v[60:61], v[122:123] op_sel_hi:[1,0]
	v_pk_mul_f32 v[18:19], v[62:63], v[122:123] op_sel_hi:[1,0]
	v_cvt_pk_bf16_f32 v16, v16, v17
	v_cvt_pk_bf16_f32 v17, v18, v19
	global_store_dwordx2 v[8:9], v[16:17], off offset:-512
	v_pk_mul_f32 v[16:17], v[64:65], v[122:123] op_sel_hi:[1,0]
	v_pk_mul_f32 v[18:19], v[66:67], v[122:123] op_sel_hi:[1,0]
	v_cvt_pk_bf16_f32 v16, v16, v17
	v_cvt_pk_bf16_f32 v17, v18, v19
	global_store_dwordx2 v[8:9], v[16:17], off
	v_pk_mul_f32 v[16:17], v[68:69], v[122:123] op_sel_hi:[1,0]
	v_pk_mul_f32 v[18:19], v[70:71], v[122:123] op_sel_hi:[1,0]
	v_cvt_pk_bf16_f32 v16, v16, v17
	v_cvt_pk_bf16_f32 v17, v18, v19
	global_store_dwordx2 v[8:9], v[16:17], off offset:512
	v_lshl_add_u64 v[8:9], v[8:9], 0, s[62:63]
	v_pk_mul_f32 v[16:17], v[72:73], v[124:125] op_sel_hi:[1,0]
	v_pk_mul_f32 v[18:19], v[74:75], v[124:125] op_sel_hi:[1,0]
	v_cvt_pk_bf16_f32 v16, v16, v17
	v_cvt_pk_bf16_f32 v17, v18, v19
	global_store_dwordx2 v[8:9], v[16:17], off offset:-1024
	v_pk_mul_f32 v[16:17], v[76:77], v[124:125] op_sel_hi:[1,0]
	v_pk_mul_f32 v[18:19], v[78:79], v[124:125] op_sel_hi:[1,0]
	v_cvt_pk_bf16_f32 v16, v16, v17
	v_cvt_pk_bf16_f32 v17, v18, v19
	global_store_dwordx2 v[8:9], v[16:17], off offset:-512
	v_pk_mul_f32 v[16:17], v[80:81], v[124:125] op_sel_hi:[1,0]
	v_pk_mul_f32 v[18:19], v[82:83], v[124:125] op_sel_hi:[1,0]
	v_cvt_pk_bf16_f32 v16, v16, v17
	v_cvt_pk_bf16_f32 v17, v18, v19
	global_store_dwordx2 v[8:9], v[16:17], off
	v_pk_mul_f32 v[16:17], v[84:85], v[124:125] op_sel_hi:[1,0]
	v_pk_mul_f32 v[18:19], v[86:87], v[124:125] op_sel_hi:[1,0]
	v_cvt_pk_bf16_f32 v16, v16, v17
	v_cvt_pk_bf16_f32 v17, v18, v19
	global_store_dwordx2 v[8:9], v[16:17], off offset:512
	v_lshl_add_u64 v[8:9], v[8:9], 0, s[62:63]
	v_pk_mul_f32 v[16:17], v[88:89], v[126:127] op_sel_hi:[1,0]
	v_pk_mul_f32 v[18:19], v[90:91], v[126:127] op_sel_hi:[1,0]
	v_cvt_pk_bf16_f32 v16, v16, v17
	v_cvt_pk_bf16_f32 v17, v18, v19
	global_store_dwordx2 v[8:9], v[16:17], off offset:-1024
	v_pk_mul_f32 v[16:17], v[92:93], v[126:127] op_sel_hi:[1,0]
	v_pk_mul_f32 v[18:19], v[94:95], v[126:127] op_sel_hi:[1,0]
	v_cvt_pk_bf16_f32 v16, v16, v17
	v_cvt_pk_bf16_f32 v17, v18, v19
	global_store_dwordx2 v[8:9], v[16:17], off offset:-512
	v_pk_mul_f32 v[16:17], v[96:97], v[126:127] op_sel_hi:[1,0]
	v_pk_mul_f32 v[18:19], v[98:99], v[126:127] op_sel_hi:[1,0]
	v_cvt_pk_bf16_f32 v16, v16, v17
	v_cvt_pk_bf16_f32 v17, v18, v19
	global_store_dwordx2 v[8:9], v[16:17], off
	v_pk_mul_f32 v[16:17], v[100:101], v[126:127] op_sel_hi:[1,0]
	v_pk_mul_f32 v[18:19], v[102:103], v[126:127] op_sel_hi:[1,0]
	v_cvt_pk_bf16_f32 v16, v16, v17
	v_cvt_pk_bf16_f32 v17, v18, v19
	global_store_dwordx2 v[8:9], v[16:17], off offset:512
	v_lshl_add_u64 v[8:9], v[8:9], 0, s[62:63]
	s_branch .Lnx1_top
.Lnx1_rem:
	s_cmp_gt_u32 s0, s2
	s_cbranch_scc1 .LBB0_1363

; DI void phase_norm_x(const float* src_lo, const float* src_hi, int split_row, int row0, bf16_t* xb, int gw, int ngw, int lane) {
;     for (int r = gw; r < MC; r += ngw) {
;         const int R = row0 + r; const float* src = (R < split_row ? src_lo + (size_t)R * 1024 : src_hi + (size_t)(R - split_row) * 1024);
;         f32x4 v[4]; float ss = 0.f;
; #pragma unroll
;         for (int j = 0; j < 4; ++j) { v[j] = *(const f32x4*)(src + j * 256 + lane * 4); ss += v[j][0] * v[j][0] + v[j][1] * v[j][1] + v[j][2] * v[j][2] + v[j][3] * v[j][3]; }
;         ss = wave_sum(ss); const float rs = rsqrtf(ldexpf(ss + 1024.0f * EPS, -10));
; __global__ void __launch_bounds__(512, 2) mega(Params P) {
;     ...
;                 if (nlayer == 0) phase_norm_x(P.in[I_XP + z], P.in[I_XS + z], MC, nch * MC, WSP(bf16_t, WS_VT), blk * 8 + wave, G * 8, lane);
.LBB0_1365:
.LBB0_1366:
	v_cmp_gt_i32_e32 vcc, s1, v0
	s_and_saveexec_b64 s[24:25], vcc
	v_readlane_b32 s28, v254, 52
	v_readlane_b32 s29, v254, 53
	s_movk_i32 s2, 0x3fff
	s_cbranch_execz .LBB0_1369
	v_and_b32_e32 v1, 64, v233
	v_add_u32_e32 v1, 64, v1
	v_xor_b32_e32 v2, 32, v233
	v_cmp_lt_i32_e32 vcc, v2, v1
	s_ashr_i32 s7, s6, 31
	s_lshl_b64 s[8:9], s[6:7], 3
	v_cndmask_b32_e32 v2, v233, v2, vcc
	v_lshlrev_b32_e32 v6, 2, v2
	v_xor_b32_e32 v2, 16, v233
	v_cmp_lt_i32_e32 vcc, v2, v1
	s_add_u32 s8, s66, s8
	s_addc_u32 s9, s67, s9
	v_cndmask_b32_e32 v2, v233, v2, vcc
	v_lshlrev_b32_e32 v7, 2, v2
	v_xor_b32_e32 v2, 8, v233
	v_cmp_lt_i32_e32 vcc, v2, v1
	s_load_dwordx4 s[20:23], s[8:9], 0x0
	s_lshl_b32 s8, s26, 14
	v_cndmask_b32_e32 v2, v233, v2, vcc
	v_lshlrev_b32_e32 v8, 2, v2
	v_xor_b32_e32 v2, 4, v233
	v_cmp_lt_i32_e32 vcc, v2, v1
	v_readlane_b32 s0, v254, 21
	s_add_u32 s6, s0, s6
	v_cndmask_b32_e32 v2, v233, v2, vcc
	v_lshlrev_b32_e32 v9, 2, v2
	v_xor_b32_e32 v2, 2, v233
	v_cmp_lt_i32_e32 vcc, v2, v1
	v_readlane_b32 s0, v254, 22
	v_lshlrev_b32_e32 v14, 2, v10
	v_cndmask_b32_e32 v2, v233, v2, vcc
	v_lshlrev_b32_e32 v11, 2, v2
	v_xor_b32_e32 v2, 1, v233
	v_cmp_lt_i32_e32 vcc, v2, v1
	s_addc_u32 s7, s0, s7
	v_lshlrev_b32_e32 v188, 2, v14
	v_cndmask_b32_e32 v1, v233, v2, vcc
	v_lshlrev_b32_e32 v12, 2, v1
	v_ashrrev_i32_e32 v1, 31, v0
	v_lshlrev_b64 v[4:5], 11, v[0:1]
	v_add_u32_e32 v2, s8, v0
	v_lshl_or_b32 v4, v10, 3, v4
	v_ashrrev_i32_e32 v3, 31, v2
	v_lshl_add_u64 v[4:5], s[6:7], 0, v[4:5]
	s_mov_b64 s[6:7], 0
	s_waitcnt lgkmcnt(0)
.Lnx2_top:
	v_readfirstlane_b32 s0, v0
	s_mul_i32 s9, s28, 3
	s_add_u32 s9, s9, s0
	s_cmp_gt_u32 s9, s2
	s_cbranch_scc1 .Lnx2_rem
	v_add_u32_e32 v1, s8, v0
	v_cmp_gt_i32_e32 vcc, s1, v1
	v_add_u32_e32 v1, 0xffffc000, v2
	v_mov_b32_e32 v10, s21
	v_cndmask_b32_e32 v14, v1, v2, vcc
	v_mov_b32_e32 v1, s23
	v_cndmask_b32_e32 v15, 0, v3, vcc
	v_cndmask_b32_e32 v17, v1, v10, vcc
	v_mov_b32_e32 v1, s22
	v_mov_b32_e32 v10, s20
	v_cndmask_b32_e32 v16, v1, v10, vcc
	v_lshlrev_b64 v[14:15], 12, v[14:15]
	v_lshl_add_u64 v[14:15], v[16:17], 0, v[14:15]
	v_lshl_add_u64 v[104:105], v[14:15], 0, v[188:189]
	v_add_u32_e32 v0, s28, v0
	v_lshl_add_u64 v[2:3], v[2:3], 0, s[28:29]
	global_load_dwordx4 v[40:43], v[104:105], off
	global_load_dwordx4 v[44:47], v[104:105], off offset:1024
	global_load_dwordx4 v[48:51], v[104:105], off offset:2048
	global_load_dwordx4 v[52:55], v[104:105], off offset:3072
	v_add_u32_e32 v1, s8, v0
	v_cmp_gt_i32_e32 vcc, s1, v1
	v_add_u32_e32 v1, 0xffffc000, v2
	v_mov_b32_e32 v10, s21
	v_cndmask_b32_e32 v14, v1, v2, vcc
	v_mov_b32_e32 v1, s23
	v_cndmask_b32_e32 v15, 0, v3, vcc
	v_cndmask_b32_e32 v17, v1, v10, vcc
	v_mov_b32_e32 v1, s22
	v_mov_b32_e32 v10, s20
	v_cndmask_b32_e32 v16, v1, v10, vcc
	v_lshlrev_b64 v[14:15], 12, v[14:15]
	v_lshl_add_u64 v[14:15], v[16:17], 0, v[14:15]
	v_lshl_add_u64 v[106:107], v[14:15], 0, v[188:189]
	v_add_u32_e32 v0, s28, v0
	v_lshl_add_u64 v[2:3], v[2:3], 0, s[28:29]
	global_load_dwordx4 v[56:59], v[106:107], off
	global_load_dwordx4 v[60:63], v[106:107], off offset:1024
	global_load_dwordx4 v[64:67], v[106:107], off offset:2048
	global_load_dwordx4 v[68:71], v[106:107], off offset:3072
	v_add_u32_e32 v1, s8, v0
	v_cmp_gt_i32_e32 vcc, s1, v1
	v_add_u32_e32 v1, 0xffffc000, v2
	v_mov_b32_e32 v10, s21
	v_cndmask_b32_e32 v14, v1, v2, vcc
	v_mov_b32_e32 v1, s23
	v_cndmask_b32_e32 v15, 0, v3, vcc
	v_cndmask_b32_e32 v17, v1, v10, vcc
	v_mov_b32_e32 v1, s22
	v_mov_b32_e32 v10, s20
	v_cndmask_b32_e32 v16, v1, v10, vcc
	v_lshlrev_b64 v[14:15], 12, v[14:15]
	v_lshl_add_u64 v[14:15], v[16:17], 0, v[14:15]
	v_lshl_add_u64 v[108:109], v[14:15], 0, v[188:189]
	v_add_u32_e32 v0, s28, v0
	v_lshl_add_u64 v[2:3], v[2:3], 0, s[28:29]
	global_load_dwordx4 v[72:75], v[108:109], off
	global_load_dwordx4 v[76:79], v[108:109], off offset:1024
	global_load_dwordx4 v[80:83], v[108:109], off offset:2048
	global_load_dwordx4 v[84:87], v[108:109], off offset:3072
	v_add_u32_e32 v1, s8, v0
	v_cmp_gt_i32_e32 vcc, s1, v1
	v_add_u32_e32 v1, 0xffffc000, v2
	v_mov_b32_e32 v10, s21
	v_cndmask_b32_e32 v14, v1, v2, vcc
	v_mov_b32_e32 v1, s23
	v_cndmask_b32_e32 v15, 0, v3, vcc
	v_cndmask_b32_e32 v17, v1, v10, vcc
	v_mov_b32_e32 v1, s22
	v_mov_b32_e32 v10, s20
	v_cndmask_b32_e32 v16, v1, v10, vcc
	v_lshlrev_b64 v[14:15], 12, v[14:15]
	v_lshl_add_u64 v[14:15], v[16:17], 0, v[14:15]
	v_lshl_add_u64 v[110:111], v[14:15], 0, v[188:189]
	v_add_u32_e32 v0, s28, v0
	v_lshl_add_u64 v[2:3], v[2:3], 0, s[28:29]
	global_load_dwordx4 v[88:91], v[110:111], off
	global_load_dwordx4 v[92:95], v[110:111], off offset:1024
	global_load_dwordx4 v[96:99], v[110:111], off offset:2048
	global_load_dwordx4 v[100:103], v[110:111], off offset:3072
	s_waitcnt vmcnt(12)
	v_mul_f32_e32 v112, v40, v40
	v_fmac_f32_e32 v112, v41, v41
	v_fmac_f32_e32 v112, v42, v42
	v_fmac_f32_e32 v112, v43, v43
	v_fmac_f32_e32 v112, v44, v44
	v_fmac_f32_e32 v112, v45, v45
	v_fmac_f32_e32 v112, v46, v46
	v_fmac_f32_e32 v112, v47, v47
	v_fmac_f32_e32 v112, v48, v48
	v_fmac_f32_e32 v112, v49, v49
	v_fmac_f32_e32 v112, v50, v50
	v_fmac_f32_e32 v112, v51, v51
	v_fmac_f32_e32 v112, v52, v52
	v_fmac_f32_e32 v112, v53, v53
	v_fmac_f32_e32 v112, v54, v54
	v_fmac_f32_e32 v112, v55, v55
	s_waitcnt vmcnt(8)
	v_mul_f32_e32 v113, v56, v56
	v_fmac_f32_e32 v113, v57, v57
	v_fmac_f32_e32 v113, v58, v58
	v_fmac_f32_e32 v113, v59, v59
	v_fmac_f32_e32 v113, v60, v60
	v_fmac_f32_e32 v113, v61, v61
	v_fmac_f32_e32 v113, v62, v62
	v_fmac_f32_e32 v113, v63, v63
	v_fmac_f32_e32 v113, v64, v64
	v_fmac_f32_e32 v113, v65, v65
	v_fmac_f32_e32 v113, v66, v66
	v_fmac_f32_e32 v113, v67, v67
	v_fmac_f32_e32 v113, v68, v68
	v_fmac_f32_e32 v113, v69, v69
	v_fmac_f32_e32 v113, v70, v70
	v_fmac_f32_e32 v113, v71, v71
	s_waitcnt vmcnt(4)
; DI void phase_norm_x(const float* src_lo, const float* src_hi, int split_row, int row0, bf16_t* xb, int gw, int ngw, int lane) {
;     ...
;         f32x4 v[4]; float ss = 0.f;
; #pragma unroll
;         for (int j = 0; j < 4; ++j) { v[j] = *(const f32x4*)(src + j * 256 + lane * 4); ss += v[j][0] * v[j][0] + v[j][1] * v[j][1] + v[j][2] * v[j][2] + v[j][3] * v[j][3]; }
;         ss = wave_sum(ss); const float rs = rsqrtf(ldexpf(ss + 1024.0f * EPS, -10));
	v_mul_f32_e32 v114, v72, v72
	v_fmac_f32_e32 v114, v73, v73
	v_fmac_f32_e32 v114, v74, v74
	v_fmac_f32_e32 v114, v75, v75
	v_fmac_f32_e32 v114, v76, v76
	v_fmac_f32_e32 v114, v77, v77
	v_fmac_f32_e32 v114, v78, v78
	v_fmac_f32_e32 v114, v79, v79
	v_fmac_f32_e32 v114, v80, v80
	v_fmac_f32_e32 v114, v81, v81
	v_fmac_f32_e32 v114, v82, v82
	v_fmac_f32_e32 v114, v83, v83
	v_fmac_f32_e32 v114, v84, v84
	v_fmac_f32_e32 v114, v85, v85
	v_fmac_f32_e32 v114, v86, v86
	v_fmac_f32_e32 v114, v87, v87
	s_waitcnt vmcnt(0)
	v_mul_f32_e32 v115, v88, v88
	v_fmac_f32_e32 v115, v89, v89
	v_fmac_f32_e32 v115, v90, v90
	v_fmac_f32_e32 v115, v91, v91
	v_fmac_f32_e32 v115, v92, v92
	v_fmac_f32_e32 v115, v93, v93
	v_fmac_f32_e32 v115, v94, v94
	v_fmac_f32_e32 v115, v95, v95
	v_fmac_f32_e32 v115, v96, v96
	v_fmac_f32_e32 v115, v97, v97
	v_fmac_f32_e32 v115, v98, v98
	v_fmac_f32_e32 v115, v99, v99
	v_fmac_f32_e32 v115, v100, v100
	v_fmac_f32_e32 v115, v101, v101
	v_fmac_f32_e32 v115, v102, v102
	v_fmac_f32_e32 v115, v103, v103
	ds_bpermute_b32 v116, v6, v112
	ds_bpermute_b32 v117, v6, v113
	ds_bpermute_b32 v118, v6, v114
	ds_bpermute_b32 v119, v6, v115
	s_waitcnt lgkmcnt(0)
	v_add_f32_e32 v112, v112, v116
	v_add_f32_e32 v113, v113, v117
	v_add_f32_e32 v114, v114, v118
	v_add_f32_e32 v115, v115, v119
	ds_bpermute_b32 v116, v7, v112
	ds_bpermute_b32 v117, v7, v113
	ds_bpermute_b32 v118, v7, v114
	ds_bpermute_b32 v119, v7, v115
	s_waitcnt lgkmcnt(0)
	v_add_f32_e32 v112, v112, v116
	v_add_f32_e32 v113, v113, v117
	v_add_f32_e32 v114, v114, v118
	v_add_f32_e32 v115, v115, v119
	ds_bpermute_b32 v116, v8, v112
	ds_bpermute_b32 v117, v8, v113
	ds_bpermute_b32 v118, v8, v114
	ds_bpermute_b32 v119, v8, v115
	s_waitcnt lgkmcnt(0)
	v_add_f32_e32 v112, v112, v116
	v_add_f32_e32 v113, v113, v117
	v_add_f32_e32 v114, v114, v118
	v_add_f32_e32 v115, v115, v119
	ds_bpermute_b32 v116, v9, v112
	ds_bpermute_b32 v117, v9, v113
	ds_bpermute_b32 v118, v9, v114
	ds_bpermute_b32 v119, v9, v115
	s_waitcnt lgkmcnt(0)
	v_add_f32_e32 v112, v112, v116
	v_add_f32_e32 v113, v113, v117
	v_add_f32_e32 v114, v114, v118
	v_add_f32_e32 v115, v115, v119
	ds_bpermute_b32 v116, v11, v112
	ds_bpermute_b32 v117, v11, v113
	ds_bpermute_b32 v118, v11, v114
	ds_bpermute_b32 v119, v11, v115
	s_waitcnt lgkmcnt(0)
	v_add_f32_e32 v112, v112, v116
	v_add_f32_e32 v113, v113, v117
	v_add_f32_e32 v114, v114, v118
	v_add_f32_e32 v115, v115, v119
	ds_bpermute_b32 v116, v12, v112
	ds_bpermute_b32 v117, v12, v113
	ds_bpermute_b32 v118, v12, v114
	ds_bpermute_b32 v119, v12, v115
	s_waitcnt lgkmcnt(0)
; DI unsigned pk2(float lo, float hi) { const f32x2_t v = {lo, hi}; return __builtin_bit_cast(unsigned, __builtin_convertvector(v, bf16x2_t)); }
; DI void phase_norm_x(const float* src_lo, const float* src_hi, int split_row, int row0, bf16_t* xb, int gw, int ngw, int lane) {
;     ...
;         ss = wave_sum(ss); const float rs = rsqrtf(ldexpf(ss + 1024.0f * EPS, -10));
; #pragma unroll
;         for (int j = 0; j < 4; ++j) { u32x2 w; w.x = pk2(v[j][0] * rs, v[j][1] * rs); w.y = pk2(v[j][2] * rs, v[j][3] * rs); *(u32x2*)(xb + (size_t)r * 1024 + j * 256 + lane * 4) = w; }
;     }
	v_add_f32_e32 v112, v112, v116
	v_add_f32_e32 v113, v113, v117
	v_add_f32_e32 v114, v114, v118
	v_add_f32_e32 v115, v115, v119
	v_add_f32_e32 v112, 0x3a8637bd, v112
	v_ldexp_f32 v112, v112, -10
	v_cmp_gt_f32_e32 vcc, s19, v112
	v_mul_f32_e32 v116, 0x4b800000, v112
	s_nop 0
	v_cndmask_b32_e32 v112, v112, v116, vcc
	v_rsq_f32_e32 v112, v112
	s_nop 0
	v_mul_f32_e32 v116, 0x45800000, v112
	v_cndmask_b32_e32 v120, v112, v116, vcc
	v_add_f32_e32 v113, 0x3a8637bd, v113
	v_ldexp_f32 v113, v113, -10
	v_cmp_gt_f32_e32 vcc, s19, v113
	v_mul_f32_e32 v116, 0x4b800000, v113
	s_nop 0
	v_cndmask_b32_e32 v113, v113, v116, vcc
	v_rsq_f32_e32 v113, v113
	s_nop 0
	v_mul_f32_e32 v116, 0x45800000, v113
	v_cndmask_b32_e32 v122, v113, v116, vcc
	v_add_f32_e32 v114, 0x3a8637bd, v114
	v_ldexp_f32 v114, v114, -10
	v_cmp_gt_f32_e32 vcc, s19, v114
	v_mul_f32_e32 v116, 0x4b800000, v114
	s_nop 0
	v_cndmask_b32_e32 v114, v114, v116, vcc
	v_rsq_f32_e32 v114, v114
	s_nop 0
	v_mul_f32_e32 v116, 0x45800000, v114
	v_cndmask_b32_e32 v124, v114, v116, vcc
	v_add_f32_e32 v115, 0x3a8637bd, v115
	v_ldexp_f32 v115, v115, -10
	v_cmp_gt_f32_e32 vcc, s19, v115
	v_mul_f32_e32 v116, 0x4b800000, v115
	s_nop 0
	v_cndmask_b32_e32 v115, v115, v116, vcc
	v_rsq_f32_e32 v115, v115
	s_nop 0
	v_mul_f32_e32 v116, 0x45800000, v115
	v_cndmask_b32_e32 v126, v115, v116, vcc
	v_pk_mul_f32 v[16:17], v[40:41], v[120:121] op_sel_hi:[1,0]
	v_pk_mul_f32 v[18:19], v[42:43], v[120:121] op_sel_hi:[1,0]
	v_cvt_pk_bf16_f32 v16, v16, v17
	v_cvt_pk_bf16_f32 v17, v18, v19
	global_store_dwordx2 v[4:5], v[16:17], off offset:-1024
	v_pk_mul_f32 v[16:17], v[44:45], v[120:121] op_sel_hi:[1,0]
	v_pk_mul_f32 v[18:19], v[46:47], v[120:121] op_sel_hi:[1,0]
	v_cvt_pk_bf16_f32 v16, v16, v17
	v_cvt_pk_bf16_f32 v17, v18, v19
	global_store_dwordx2 v[4:5], v[16:17], off offset:-512
	v_pk_mul_f32 v[16:17], v[48:49], v[120:121] op_sel_hi:[1,0]
	v_pk_mul_f32 v[18:19], v[50:51], v[120:121] op_sel_hi:[1,0]
	v_cvt_pk_bf16_f32 v16, v16, v17
	v_cvt_pk_bf16_f32 v17, v18, v19
	global_store_dwordx2 v[4:5], v[16:17], off
	v_pk_mul_f32 v[16:17], v[52:53], v[120:121] op_sel_hi:[1,0]
	v_pk_mul_f32 v[18:19], v[54:55], v[120:121] op_sel_hi:[1,0]
	v_cvt_pk_bf16_f32 v16, v16, v17
	v_cvt_pk_bf16_f32 v17, v18, v19
	global_store_dwordx2 v[4:5], v[16:17], off offset:512
	v_lshl_add_u64 v[4:5], v[4:5], 0, s[62:63]
	v_pk_mul_f32 v[16:17], v[56:57], v[122:123] op_sel_hi:[1,0]
	v_pk_mul_f32 v[18:19], v[58:59], v[122:123] op_sel_hi:[1,0]
	v_cvt_pk_bf16_f32 v16, v16, v17
	v_cvt_pk_bf16_f32 v17, v18, v19
	global_store_dwordx2 v[4:5], v[16:17], off offset:-1024
	v_pk_mul_f32 v[16:17], v[60:61], v[122:123] op_sel_hi:[1,0]
	v_pk_mul_f32 v[18:19], v[62:63], v[122:123] op_sel_hi:[1,0]
	v_cvt_pk_bf16_f32 v16, v16, v17
	v_cvt_pk_bf16_f32 v17, v18, v19
	global_store_dwordx2 v[4:5], v[16:17], off offset:-512
	v_pk_mul_f32 v[16:17], v[64:65], v[122:123] op_sel_hi:[1,0]
	v_pk_mul_f32 v[18:19], v[66:67], v[122:123] op_sel_hi:[1,0]
	v_cvt_pk_bf16_f32 v16, v16, v17
	v_cvt_pk_bf16_f32 v17, v18, v19
	global_store_dwordx2 v[4:5], v[16:17], off
	v_pk_mul_f32 v[16:17], v[68:69], v[122:123] op_sel_hi:[1,0]
	v_pk_mul_f32 v[18:19], v[70:71], v[122:123] op_sel_hi:[1,0]
	v_cvt_pk_bf16_f32 v16, v16, v17
	v_cvt_pk_bf16_f32 v17, v18, v19
	global_store_dwordx2 v[4:5], v[16:17], off offset:512
	v_lshl_add_u64 v[4:5], v[4:5], 0, s[62:63]
	v_pk_mul_f32 v[16:17], v[72:73], v[124:125] op_sel_hi:[1,0]
	v_pk_mul_f32 v[18:19], v[74:75], v[124:125] op_sel_hi:[1,0]
	v_cvt_pk_bf16_f32 v16, v16, v17
	v_cvt_pk_bf16_f32 v17, v18, v19
	global_store_dwordx2 v[4:5], v[16:17], off offset:-1024
	v_pk_mul_f32 v[16:17], v[76:77], v[124:125] op_sel_hi:[1,0]
	v_pk_mul_f32 v[18:19], v[78:79], v[124:125] op_sel_hi:[1,0]
	v_cvt_pk_bf16_f32 v16, v16, v17
	v_cvt_pk_bf16_f32 v17, v18, v19
	global_store_dwordx2 v[4:5], v[16:17], off offset:-512
	v_pk_mul_f32 v[16:17], v[80:81], v[124:125] op_sel_hi:[1,0]
	v_pk_mul_f32 v[18:19], v[82:83], v[124:125] op_sel_hi:[1,0]
	v_cvt_pk_bf16_f32 v16, v16, v17
	v_cvt_pk_bf16_f32 v17, v18, v19
	global_store_dwordx2 v[4:5], v[16:17], off
	v_pk_mul_f32 v[16:17], v[84:85], v[124:125] op_sel_hi:[1,0]
	v_pk_mul_f32 v[18:19], v[86:87], v[124:125] op_sel_hi:[1,0]
	v_cvt_pk_bf16_f32 v16, v16, v17
	v_cvt_pk_bf16_f32 v17, v18, v19
	global_store_dwordx2 v[4:5], v[16:17], off offset:512
	v_lshl_add_u64 v[4:5], v[4:5], 0, s[62:63]
	v_pk_mul_f32 v[16:17], v[88:89], v[126:127] op_sel_hi:[1,0]
	v_pk_mul_f32 v[18:19], v[90:91], v[126:127] op_sel_hi:[1,0]
	v_cvt_pk_bf16_f32 v16, v16, v17
	v_cvt_pk_bf16_f32 v17, v18, v19
	global_store_dwordx2 v[4:5], v[16:17], off offset:-1024
	v_pk_mul_f32 v[16:17], v[92:93], v[126:127] op_sel_hi:[1,0]
	v_pk_mul_f32 v[18:19], v[94:95], v[126:127] op_sel_hi:[1,0]
	v_cvt_pk_bf16_f32 v16, v16, v17
	v_cvt_pk_bf16_f32 v17, v18, v19
	global_store_dwordx2 v[4:5], v[16:17], off offset:-512
	v_pk_mul_f32 v[16:17], v[96:97], v[126:127] op_sel_hi:[1,0]
	v_pk_mul_f32 v[18:19], v[98:99], v[126:127] op_sel_hi:[1,0]
	v_cvt_pk_bf16_f32 v16, v16, v17
	v_cvt_pk_bf16_f32 v17, v18, v19
	global_store_dwordx2 v[4:5], v[16:17], off
	v_pk_mul_f32 v[16:17], v[100:101], v[126:127] op_sel_hi:[1,0]
	v_pk_mul_f32 v[18:19], v[102:103], v[126:127] op_sel_hi:[1,0]
	v_cvt_pk_bf16_f32 v16, v16, v17
	v_cvt_pk_bf16_f32 v17, v18, v19
	global_store_dwordx2 v[4:5], v[16:17], off offset:512
	v_lshl_add_u64 v[4:5], v[4:5], 0, s[62:63]
	s_branch .Lnx2_top

; DI int opq0() { int z = 0; asm volatile("" : "+s"(z)); return z; }
; __global__ void __launch_bounds__(512, 2) mega(Params P) {
;     ...
;     {
;         const int z = opq0(); TID_VARS; const float* gf = P.in[I_GFIN + z];
;         for (int r = blk * 8 + wave; r < MTOT; r += G * 8) {
;             float* row = P.out + z + (size_t)r * 1024; f32x4 v[4]; float ss = 0.f;
; #pragma unroll
;             for (int j = 0; j < 4; ++j) { v[j] = *(const f32x4*)(row + j * 256 + lane * 4); ss += v[j][0] * v[j][0] + v[j][1] * v[j][1] + v[j][2] * v[j][2] + v[j][3] * v[j][3]; }
;             ss = wave_sum(ss); const float rs = rsqrtf(ldexpf(ss + 1024.0f * EPS, -10));
.LBB0_1430:
	s_mov_b32 s2, 0
	v_readlane_b32 s8, v254, 23
	v_ashrrev_i32_e32 v2, 6, v232
	s_mov_b32 s0, 0xc000
	v_add_u32_e32 v4, s8, v2
	v_readlane_b32 s9, v254, 24
	v_cmp_gt_i32_e32 vcc, s0, v4
	s_and_saveexec_b64 s[0:1], vcc
	v_readlane_b32 s10, v254, 19
	v_readlane_b32 s11, v254, 20
	s_cbranch_execz .LBB0_1433
	v_and_b32_e32 v0, 64, v233
	v_add_u32_e32 v0, 64, v0
	v_xor_b32_e32 v1, 32, v233
	v_cmp_lt_i32_e32 vcc, v1, v0
	s_ashr_i32 s3, s2, 31
	s_lshl_b64 s[0:1], s[2:3], 3
	v_cndmask_b32_e32 v1, v233, v1, vcc
	v_lshlrev_b32_e32 v5, 2, v1
	v_xor_b32_e32 v1, 16, v233
	v_cmp_lt_i32_e32 vcc, v1, v0
	s_add_u32 s0, s66, s0
	s_addc_u32 s1, s67, s1
	v_cndmask_b32_e32 v1, v233, v1, vcc
	v_lshlrev_b32_e32 v6, 2, v1
	v_xor_b32_e32 v1, 8, v233
	v_cmp_lt_i32_e32 vcc, v1, v0
	s_load_dwordx2 s[4:5], s[0:1], 0xc0
	s_load_dwordx2 s[6:7], s[66:67], 0xc8
	v_cndmask_b32_e32 v1, v233, v1, vcc
	v_lshlrev_b32_e32 v7, 2, v1
	v_xor_b32_e32 v1, 4, v233
	v_cmp_lt_i32_e32 vcc, v1, v0
	v_ashrrev_i32_e32 v3, 31, v2
	v_lshl_add_u64 v[2:3], v[2:3], 0, s[8:9]
	v_cndmask_b32_e32 v1, v233, v1, vcc
	v_lshlrev_b32_e32 v8, 2, v1
	v_xor_b32_e32 v1, 2, v233
	v_cmp_lt_i32_e32 vcc, v1, v0
	s_lshl_b64 s[0:1], s[2:3], 2
	v_lshlrev_b64 v[2:3], 12, v[2:3]
	v_cndmask_b32_e32 v1, v233, v1, vcc
	v_lshlrev_b32_e32 v9, 2, v1
	v_xor_b32_e32 v1, 1, v233
	v_cmp_lt_i32_e32 vcc, v1, v0
	v_and_b32_e32 v11, 63, v232
	s_waitcnt lgkmcnt(0)
	s_add_u32 s0, s6, s0
	v_cndmask_b32_e32 v0, v233, v1, vcc
	v_lshlrev_b32_e32 v10, 2, v0
	v_lshlrev_b32_e32 v0, 4, v232
	v_lshl_or_b32 v2, v11, 4, v2
	s_addc_u32 s1, s7, s1
	v_and_b32_e32 v0, 0x3f0, v0
	v_mov_b32_e32 v1, 0
	v_lshl_add_u64 v[2:3], s[0:1], 0, v[2:3]
	s_mov_b64 s[0:1], 0xc00
	v_lshl_add_u64 v[0:1], s[4:5], 0, v[0:1]
	v_lshl_add_u64 v[2:3], v[2:3], 0, s[0:1]
	s_mov_b64 s[0:1], 0
	s_mov_b32 s2, 0x800000
	s_mov_b32 s3, 0xbfff
	global_load_dwordx4 v[48:51], v[0:1], off
	global_load_dwordx4 v[52:55], v[0:1], off offset:1024
	global_load_dwordx4 v[56:59], v[0:1], off offset:2048
	global_load_dwordx4 v[60:63], v[0:1], off offset:3072
	s_mul_i32 s4, s34, 3
.Lfn_loop4:
	v_readfirstlane_b32 s5, v4
	s_add_u32 s6, s5, s4
	s_cmp_gt_u32 s6, s3
	s_cbranch_scc1 .Lfn_rem
	v_lshl_add_u64 v[64:65], v[2:3], 0, s[10:11]
	v_lshl_add_u64 v[66:67], v[64:65], 0, s[10:11]
	v_lshl_add_u64 v[68:69], v[66:67], 0, s[10:11]
	global_load_dwordx4 v[12:15], v[2:3], off offset:-3072
	global_load_dwordx4 v[16:19], v[2:3], off offset:-2048
	global_load_dwordx4 v[20:23], v[2:3], off offset:-1024
	global_load_dwordx4 v[24:27], v[2:3], off
	global_load_dwordx4 v[70:73], v[64:65], off offset:-3072
	global_load_dwordx4 v[74:77], v[64:65], off offset:-2048
	global_load_dwordx4 v[78:81], v[64:65], off offset:-1024
	global_load_dwordx4 v[82:85], v[64:65], off
	global_load_dwordx4 v[86:89], v[66:67], off offset:-3072
	global_load_dwordx4 v[90:93], v[66:67], off offset:-2048
	global_load_dwordx4 v[94:97], v[66:67], off offset:-1024
	global_load_dwordx4 v[98:101], v[66:67], off
	global_load_dwordx4 v[102:105], v[68:69], off offset:-3072
	global_load_dwordx4 v[106:109], v[68:69], off offset:-2048
	global_load_dwordx4 v[110:113], v[68:69], off offset:-1024
	global_load_dwordx4 v[114:117], v[68:69], off
	s_waitcnt vmcnt(12)
	v_mul_f32_e32 v11, v12, v12
	v_fmac_f32_e32 v11, v13, v13
	v_fmac_f32_e32 v11, v14, v14
	v_fmac_f32_e32 v11, v15, v15
	v_fmac_f32_e32 v11, v16, v16
	v_fmac_f32_e32 v11, v17, v17
	v_fmac_f32_e32 v11, v18, v18
	v_fmac_f32_e32 v11, v19, v19
	v_fmac_f32_e32 v11, v20, v20
	v_fmac_f32_e32 v11, v21, v21
	v_fmac_f32_e32 v11, v22, v22
	v_fmac_f32_e32 v11, v23, v23
	v_fmac_f32_e32 v11, v24, v24
	v_fmac_f32_e32 v11, v25, v25
	v_fmac_f32_e32 v11, v26, v26
	v_fmac_f32_e32 v11, v27, v27
	s_waitcnt vmcnt(8)
	v_mul_f32_e32 v118, v70, v70
	v_fmac_f32_e32 v118, v71, v71
	v_fmac_f32_e32 v118, v72, v72
	v_fmac_f32_e32 v118, v73, v73
	v_fmac_f32_e32 v118, v74, v74
	v_fmac_f32_e32 v118, v75, v75
	v_fmac_f32_e32 v118, v76, v76
	v_fmac_f32_e32 v118, v77, v77
	v_fmac_f32_e32 v118, v78, v78
	v_fmac_f32_e32 v118, v79, v79
	v_fmac_f32_e32 v118, v80, v80
	v_fmac_f32_e32 v118, v81, v81
	v_fmac_f32_e32 v118, v82, v82
	v_fmac_f32_e32 v118, v83, v83
	v_fmac_f32_e32 v118, v84, v84
	v_fmac_f32_e32 v118, v85, v85
	s_waitcnt vmcnt(4)
	v_mul_f32_e32 v119, v86, v86
	v_fmac_f32_e32 v119, v87, v87
	v_fmac_f32_e32 v119, v88, v88
	v_fmac_f32_e32 v119, v89, v89
	v_fmac_f32_e32 v119, v90, v90
	v_fmac_f32_e32 v119, v91, v91
	v_fmac_f32_e32 v119, v92, v92
	v_fmac_f32_e32 v119, v93, v93
	v_fmac_f32_e32 v119, v94, v94
	v_fmac_f32_e32 v119, v95, v95
	v_fmac_f32_e32 v119, v96, v96
	v_fmac_f32_e32 v119, v97, v97
	v_fmac_f32_e32 v119, v98, v98
	v_fmac_f32_e32 v119, v99, v99
	v_fmac_f32_e32 v119, v100, v100
	v_fmac_f32_e32 v119, v101, v101
	s_waitcnt vmcnt(0)
	v_mul_f32_e32 v120, v102, v102
	v_fmac_f32_e32 v120, v103, v103
	v_fmac_f32_e32 v120, v104, v104
	v_fmac_f32_e32 v120, v105, v105
	v_fmac_f32_e32 v120, v106, v106
	v_fmac_f32_e32 v120, v107, v107
	v_fmac_f32_e32 v120, v108, v108
	v_fmac_f32_e32 v120, v109, v109
	v_fmac_f32_e32 v120, v110, v110
	v_fmac_f32_e32 v120, v111, v111
	v_fmac_f32_e32 v120, v112, v112
	v_fmac_f32_e32 v120, v113, v113
	v_fmac_f32_e32 v120, v114, v114
	v_fmac_f32_e32 v120, v115, v115
	v_fmac_f32_e32 v120, v116, v116
	v_fmac_f32_e32 v120, v117, v117
	ds_bpermute_b32 v32, v5, v11
	ds_bpermute_b32 v33, v5, v118
	ds_bpermute_b32 v34, v5, v119
	ds_bpermute_b32 v35, v5, v120
	s_waitcnt lgkmcnt(0)
	v_add_f32_e32 v11, v11, v32
	v_add_f32_e32 v118, v118, v33
	v_add_f32_e32 v119, v119, v34
	v_add_f32_e32 v120, v120, v35
	ds_bpermute_b32 v32, v6, v11
	ds_bpermute_b32 v33, v6, v118
	ds_bpermute_b32 v34, v6, v119
	ds_bpermute_b32 v35, v6, v120
	s_waitcnt lgkmcnt(0)
; __global__ void __launch_bounds__(512, 2) mega(Params P) {
;     ...
;             ss = wave_sum(ss); const float rs = rsqrtf(ldexpf(ss + 1024.0f * EPS, -10));
; #pragma unroll
;             for (int j = 0; j < 4; ++j) { const f32x4 gg = *(const f32x4*)(gf + j * 256 + lane * 4); *(f32x4*)(row + j * 256 + lane * 4) = v[j] * rs * gg; }
;         }
	v_add_f32_e32 v11, v11, v32
	v_add_f32_e32 v118, v118, v33
	v_add_f32_e32 v119, v119, v34
	v_add_f32_e32 v120, v120, v35
	ds_bpermute_b32 v32, v7, v11
	ds_bpermute_b32 v33, v7, v118
	ds_bpermute_b32 v34, v7, v119
	ds_bpermute_b32 v35, v7, v120
	s_waitcnt lgkmcnt(0)
	v_add_f32_e32 v11, v11, v32
	v_add_f32_e32 v118, v118, v33
	v_add_f32_e32 v119, v119, v34
	v_add_f32_e32 v120, v120, v35
	ds_bpermute_b32 v32, v8, v11
	ds_bpermute_b32 v33, v8, v118
	ds_bpermute_b32 v34, v8, v119
	ds_bpermute_b32 v35, v8, v120
	s_waitcnt lgkmcnt(0)
	v_add_f32_e32 v11, v11, v32
	v_add_f32_e32 v118, v118, v33
	v_add_f32_e32 v119, v119, v34
	v_add_f32_e32 v120, v120, v35
	ds_bpermute_b32 v32, v9, v11
	ds_bpermute_b32 v33, v9, v118
	ds_bpermute_b32 v34, v9, v119
	ds_bpermute_b32 v35, v9, v120
	s_waitcnt lgkmcnt(0)
	v_add_f32_e32 v11, v11, v32
	v_add_f32_e32 v118, v118, v33
	v_add_f32_e32 v119, v119, v34
	v_add_f32_e32 v120, v120, v35
	ds_bpermute_b32 v32, v10, v11
	ds_bpermute_b32 v33, v10, v118
	ds_bpermute_b32 v34, v10, v119
	ds_bpermute_b32 v35, v10, v120
	s_waitcnt lgkmcnt(0)
	v_add_f32_e32 v11, v11, v32
	v_add_f32_e32 v118, v118, v33
	v_add_f32_e32 v119, v119, v34
	v_add_f32_e32 v120, v120, v35
	v_add_f32_e32 v11, 0x3a8637bd, v11
	v_ldexp_f32 v11, v11, -10
	v_mul_f32_e32 v32, 0x4b800000, v11
	v_cmp_gt_f32_e32 vcc, s2, v11
	s_nop 1
	v_cndmask_b32_e32 v11, v11, v32, vcc
	v_rsq_f32_e32 v11, v11
	s_nop 0
	v_mul_f32_e32 v32, 0x45800000, v11
	v_cndmask_b32_e32 v36, v11, v32, vcc
	v_add_f32_e32 v118, 0x3a8637bd, v118
	v_ldexp_f32 v118, v118, -10
	v_mul_f32_e32 v32, 0x4b800000, v118
	v_cmp_gt_f32_e32 vcc, s2, v118
	s_nop 1
	v_cndmask_b32_e32 v118, v118, v32, vcc
	v_rsq_f32_e32 v118, v118
	s_nop 0
	v_mul_f32_e32 v32, 0x45800000, v118
	v_cndmask_b32_e32 v38, v118, v32, vcc
	v_add_f32_e32 v119, 0x3a8637bd, v119
	v_ldexp_f32 v119, v119, -10
	v_mul_f32_e32 v32, 0x4b800000, v119
	v_cmp_gt_f32_e32 vcc, s2, v119
	s_nop 1
	v_cndmask_b32_e32 v119, v119, v32, vcc
	v_rsq_f32_e32 v119, v119
	s_nop 0
	v_mul_f32_e32 v32, 0x45800000, v119
	v_cndmask_b32_e32 v40, v119, v32, vcc
	v_add_f32_e32 v120, 0x3a8637bd, v120
	v_ldexp_f32 v120, v120, -10
	v_mul_f32_e32 v32, 0x4b800000, v120
	v_cmp_gt_f32_e32 vcc, s2, v120
	s_nop 1
	v_cndmask_b32_e32 v120, v120, v32, vcc
	v_rsq_f32_e32 v120, v120
	s_nop 0
	v_mul_f32_e32 v32, 0x45800000, v120
	v_cndmask_b32_e32 v42, v120, v32, vcc
	v_pk_mul_f32 v[12:13], v[36:37], v[12:13] op_sel_hi:[0,1]
	v_pk_mul_f32 v[14:15], v[36:37], v[14:15] op_sel_hi:[0,1]
	v_pk_mul_f32 v[12:13], v[12:13], v[48:49]
	v_pk_mul_f32 v[14:15], v[14:15], v[50:51]
	global_store_dwordx4 v[2:3], v[12:15], off offset:-3072
	v_pk_mul_f32 v[16:17], v[36:37], v[16:17] op_sel_hi:[0,1]
	v_pk_mul_f32 v[18:19], v[36:37], v[18:19] op_sel_hi:[0,1]
	v_pk_mul_f32 v[16:17], v[16:17], v[52:53]
	v_pk_mul_f32 v[18:19], v[18:19], v[54:55]
	global_store_dwordx4 v[2:3], v[16:19], off offset:-2048
	v_pk_mul_f32 v[20:21], v[36:37], v[20:21] op_sel_hi:[0,1]
	v_pk_mul_f32 v[22:23], v[36:37], v[22:23] op_sel_hi:[0,1]
	v_pk_mul_f32 v[20:21], v[20:21], v[56:57]
	v_pk_mul_f32 v[22:23], v[22:23], v[58:59]
	global_store_dwordx4 v[2:3], v[20:23], off offset:-1024
	v_pk_mul_f32 v[24:25], v[36:37], v[24:25] op_sel_hi:[0,1]
	v_pk_mul_f32 v[26:27], v[36:37], v[26:27] op_sel_hi:[0,1]
	v_pk_mul_f32 v[24:25], v[24:25], v[60:61]
	v_pk_mul_f32 v[26:27], v[26:27], v[62:63]
	global_store_dwordx4 v[2:3], v[24:27], off
	v_pk_mul_f32 v[70:71], v[38:39], v[70:71] op_sel_hi:[0,1]
	v_pk_mul_f32 v[72:73], v[38:39], v[72:73] op_sel_hi:[0,1]
	v_pk_mul_f32 v[70:71], v[70:71], v[48:49]
	v_pk_mul_f32 v[72:73], v[72:73], v[50:51]
	global_store_dwordx4 v[64:65], v[70:73], off offset:-3072
	v_pk_mul_f32 v[74:75], v[38:39], v[74:75] op_sel_hi:[0,1]
	v_pk_mul_f32 v[76:77], v[38:39], v[76:77] op_sel_hi:[0,1]
	v_pk_mul_f32 v[74:75], v[74:75], v[52:53]
	v_pk_mul_f32 v[76:77], v[76:77], v[54:55]
	global_store_dwordx4 v[64:65], v[74:77], off offset:-2048
	v_pk_mul_f32 v[78:79], v[38:39], v[78:79] op_sel_hi:[0,1]
	v_pk_mul_f32 v[80:81], v[38:39], v[80:81] op_sel_hi:[0,1]
	v_pk_mul_f32 v[78:79], v[78:79], v[56:57]
	v_pk_mul_f32 v[80:81], v[80:81], v[58:59]
	global_store_dwordx4 v[64:65], v[78:81], off offset:-1024
	v_pk_mul_f32 v[82:83], v[38:39], v[82:83] op_sel_hi:[0,1]
	v_pk_mul_f32 v[84:85], v[38:39], v[84:85] op_sel_hi:[0,1]
	v_pk_mul_f32 v[82:83], v[82:83], v[60:61]
	v_pk_mul_f32 v[84:85], v[84:85], v[62:63]
	global_store_dwordx4 v[64:65], v[82:85], off
	v_pk_mul_f32 v[86:87], v[40:41], v[86:87] op_sel_hi:[0,1]
	v_pk_mul_f32 v[88:89], v[40:41], v[88:89] op_sel_hi:[0,1]
	v_pk_mul_f32 v[86:87], v[86:87], v[48:49]
	v_pk_mul_f32 v[88:89], v[88:89], v[50:51]
	global_store_dwordx4 v[66:67], v[86:89], off offset:-3072
	v_pk_mul_f32 v[90:91], v[40:41], v[90:91] op_sel_hi:[0,1]
	v_pk_mul_f32 v[92:93], v[40:41], v[92:93] op_sel_hi:[0,1]
	v_pk_mul_f32 v[90:91], v[90:91], v[52:53]
	v_pk_mul_f32 v[92:93], v[92:93], v[54:55]
	global_store_dwordx4 v[66:67], v[90:93], off offset:-2048
	v_pk_mul_f32 v[94:95], v[40:41], v[94:95] op_sel_hi:[0,1]
	v_pk_mul_f32 v[96:97], v[40:41], v[96:97] op_sel_hi:[0,1]
	v_pk_mul_f32 v[94:95], v[94:95], v[56:57]
	v_pk_mul_f32 v[96:97], v[96:97], v[58:59]
	global_store_dwordx4 v[66:67], v[94:97], off offset:-1024
	v_pk_mul_f32 v[98:99], v[40:41], v[98:99] op_sel_hi:[0,1]
	v_pk_mul_f32 v[100:101], v[40:41], v[100:101] op_sel_hi:[0,1]
	v_pk_mul_f32 v[98:99], v[98:99], v[60:61]
	v_pk_mul_f32 v[100:101], v[100:101], v[62:63]
	global_store_dwordx4 v[66:67], v[98:101], off
	v_pk_mul_f32 v[102:103], v[42:43], v[102:103] op_sel_hi:[0,1]
	v_pk_mul_f32 v[104:105], v[42:43], v[104:105] op_sel_hi:[0,1]
	v_pk_mul_f32 v[102:103], v[102:103], v[48:49]
	v_pk_mul_f32 v[104:105], v[104:105], v[50:51]
	global_store_dwordx4 v[68:69], v[102:105], off offset:-3072
	v_pk_mul_f32 v[106:107], v[42:43], v[106:107] op_sel_hi:[0,1]
	v_pk_mul_f32 v[108:109], v[42:43], v[108:109] op_sel_hi:[0,1]
	v_pk_mul_f32 v[106:107], v[106:107], v[52:53]
	v_pk_mul_f32 v[108:109], v[108:109], v[54:55]
	global_store_dwordx4 v[68:69], v[106:109], off offset:-2048
	v_pk_mul_f32 v[110:111], v[42:43], v[110:111] op_sel_hi:[0,1]
	v_pk_mul_f32 v[112:113], v[42:43], v[112:113] op_sel_hi:[0,1]
	v_pk_mul_f32 v[110:111], v[110:111], v[56:57]
	v_pk_mul_f32 v[112:113], v[112:113], v[58:59]
	global_store_dwordx4 v[68:69], v[110:113], off offset:-1024
	v_pk_mul_f32 v[114:115], v[42:43], v[114:115] op_sel_hi:[0,1]
	v_pk_mul_f32 v[116:117], v[42:43], v[116:117] op_sel_hi:[0,1]
	v_pk_mul_f32 v[114:115], v[114:115], v[60:61]
	v_pk_mul_f32 v[116:117], v[116:117], v[62:63]
	global_store_dwordx4 v[68:69], v[114:117], off
	s_lshl_b32 s6, s34, 2
	v_add_u32_e32 v4, s6, v4
	v_lshl_add_u64 v[2:3], v[68:69], 0, s[10:11]
	s_branch .Lfn_loop4
.Lfn_rem:
	s_cmp_gt_u32 s5, s3
	s_cbranch_scc1 .LBB0_1433
